# GEMM phase start: zero fill of the 109 accumulators untouched by the prologue hoisted ahead of the seam completion point
# speedup vs baseline: 1.0074x; 1.0074x over previous
.LBB0_320:
	s_andn2_b64 vcc, exec, s[0:1]
	s_cbranch_vccnz .LBB0_399
	v_bfe_i32 v2, v12, 27, 1
	v_lshlrev_b32_e32 v0, 4, v12
	v_lshrrev_b32_e32 v2, 22, v2
	v_add_u32_e32 v2, v0, v2
	v_and_b32_e32 v2, 0xfffffc00, v2
	v_sub_u32_e32 v2, v0, v2
	v_ashrrev_i32_e32 v1, 31, v12
	s_waitcnt lgkmcnt(0)
	v_lshrrev_b32_e32 v3, 4, v2
	v_lshrrev_b32_e32 v1, 26, v1
	v_bitop3_b32 v2, v3, v2, 32 bitop3:0x6c
	v_add_u32_e32 v1, v12, v1
	v_ashrrev_i32_e32 v4, 31, v2
	v_ashrrev_i32_e32 v1, 6, v1
	v_lshrrev_b32_e32 v4, 26, v4
	v_lshlrev_b32_e32 v3, 3, v1
	v_add_u32_e32 v4, v2, v4
	v_and_b32_e32 v3, -16, v3
	v_ashrrev_i32_e32 v5, 6, v4
	v_lshlrev_b32_e32 v1, 5, v1
	v_add_u32_e32 v3, v5, v3
	v_and_b32_e32 v13, 32, v1
	v_and_b32_e32 v1, 0xc0, v4
	v_sub_u32_e32 v1, v2, v1
	v_lshlrev_b32_e32 v2, 1, v3
	v_lshrrev_b32_e32 v4, 2, v3
	v_and_b32_e32 v5, 3, v5
	s_mov_b32 s1, 0x7fffffe0
	v_ashrrev_i16_sdwa v1, v155, sext(v1) dst_sel:DWORD dst_unused:UNUSED_PAD src0_sel:DWORD src1_sel:BYTE_0
	v_and_b32_e32 v2, 24, v2
	v_and_b32_e32 v4, 4, v4
	v_and_or_b32 v5, v3, s1, v5
	v_bfe_i32 v14, v1, 0, 16
	v_or3_b32 v2, v5, v4, v2
	v_readlane_b32 s52, v233, 50
	v_add_u32_e32 v1, v13, v14
	v_add_u32_e32 v0, 0x2000, v0
	v_mul_lo_u32 v15, v3, s52
	v_mul_lo_u32 v2, v2, s52
	v_add_lshl_u32 v130, v1, v15, 1
	v_add_lshl_u32 v96, v2, v1, 1
	v_ashrrev_i32_e32 v1, 31, v0
	v_lshrrev_b32_e32 v1, 22, v1
	v_add_u32_e32 v1, v0, v1
	v_ashrrev_i32_e32 v1, 10, v1
	v_readlane_b32 s53, v233, 51
	v_mul_i32_i24_e32 v2, 0x400, v1
	v_sub_u32_e32 v0, v0, v2
	s_mov_b32 s53, s47
	v_lshrrev_b32_e32 v2, 4, v0
	s_lshl_b64 s[72:73], s[52:53], 9
	s_ashr_i32 s9, s46, 31
	v_bitop3_b32 v0, v2, v0, 32 bitop3:0x6c
	s_mul_i32 s9, s72, s9
	s_mul_hi_u32 s39, s72, s46
	v_ashrrev_i32_e32 v3, 31, v0
	s_add_i32 s9, s39, s9
	s_lshr_b32 s39, s52, 23
	v_writelane_b32 v232, s76, 22
	v_lshrrev_b32_e32 v3, 26, v3
	s_mul_i32 s40, s39, s46
	v_writelane_b32 v232, s77, 23
	v_lshlrev_b32_e32 v2, 3, v1
	v_add_u32_e32 v3, v0, v3
	s_add_i32 s43, s9, s40
	s_ashr_i32 s9, s69, 31
	v_writelane_b32 v232, s78, 24
	v_and_b32_e32 v2, -16, v2
	v_ashrrev_i32_e32 v4, 6, v3
	s_mul_i32 s9, s72, s9
	s_mul_hi_u32 s40, s72, s69
	v_writelane_b32 v232, s79, 25
	s_ashr_i32 s0, s38, 6
	v_add_u32_e32 v2, v4, v2
	v_lshlrev_b32_e32 v1, 5, v1
	v_and_b32_e32 v4, 3, v4
	s_add_i32 s9, s40, s9
	s_mul_i32 s39, s39, s69
	v_and_b32_e32 v16, 32, v1
	v_and_b32_e32 v1, 0xc0, v3
	v_and_or_b32 v4, v2, s1, v4
	s_ashr_i32 s1, s38, 8
	s_lshl_b64 s[34:35], s[52:53], 8
	s_lshl_b32 s8, s0, 10
	s_add_i32 s9, s9, s39
	s_mul_i32 s39, s72, s69
	v_readlane_b32 s40, v232, 11
	v_sub_u32_e32 v0, v0, v1
	v_lshlrev_b32_e32 v1, 1, v2
	v_lshrrev_b32_e32 v3, 2, v2
	v_readlane_b32 s41, v232, 12
	s_add_u32 s78, s40, s39
	v_ashrrev_i16_sdwa v0, v155, sext(v0) dst_sel:DWORD dst_unused:UNUSED_PAD src0_sel:DWORD src1_sel:BYTE_0
	v_and_b32_e32 v1, 24, v1
	v_and_b32_e32 v3, 4, v3
	s_addc_u32 s79, s41, s9
	s_add_i32 s9, s8, 0
	v_bfe_i32 v17, v0, 0, 16
	v_or3_b32 v1, v4, v3, v1
	v_mov_b32_e32 v19, 0
	v_mov_b32_e32 v20, 0
	v_mov_b32_e32 v21, 0
	v_mov_b32_e32 v22, 0
	v_mov_b32_e32 v23, 0
	v_mov_b32_e32 v24, 0
	v_mov_b32_e32 v25, 0
	v_mov_b32_e32 v26, 0
	v_mov_b32_e32 v27, 0
	v_mov_b32_e32 v28, 0
	v_mov_b32_e32 v29, 0
	v_mov_b32_e32 v30, 0
	v_mov_b32_e32 v31, 0
	v_mov_b32_e32 v32, 0
	v_mov_b32_e32 v33, 0
	v_mov_b32_e32 v34, 0
	v_mov_b32_e32 v35, 0
	v_mov_b32_e32 v36, 0
	v_mov_b32_e32 v37, 0
	v_mov_b32_e32 v38, 0
	v_mov_b32_e32 v39, 0
	v_mov_b32_e32 v40, 0
	v_mov_b32_e32 v41, 0
	v_mov_b32_e32 v42, 0
	v_mov_b32_e32 v43, 0
	v_mov_b32_e32 v44, 0
	v_mov_b32_e32 v45, 0
	v_mov_b32_e32 v46, 0
	v_mov_b32_e32 v47, 0
	v_mov_b32_e32 v48, 0
	v_mov_b32_e32 v49, 0
	v_mov_b32_e32 v50, 0
	v_mov_b32_e32 v51, 0
	v_mov_b32_e32 v52, 0
	v_mov_b32_e32 v53, 0
	v_mov_b32_e32 v54, 0
	v_mov_b32_e32 v55, 0
	v_mov_b32_e32 v56, 0
	v_mov_b32_e32 v57, 0
	v_mov_b32_e32 v58, 0
	v_mov_b32_e32 v59, 0
	v_mov_b32_e32 v60, 0
	v_mov_b32_e32 v61, 0
	v_mov_b32_e32 v62, 0
	v_mov_b32_e32 v63, 0
	v_mov_b32_e32 v64, 0
	v_mov_b32_e32 v65, 0
	v_mov_b32_e32 v66, 0
	v_mov_b32_e32 v67, 0
	v_mov_b32_e32 v68, 0
	v_mov_b32_e32 v69, 0
	v_mov_b32_e32 v70, 0
	v_mov_b32_e32 v71, 0
	v_mov_b32_e32 v72, 0
	v_mov_b32_e32 v73, 0
	v_mov_b32_e32 v74, 0
	v_mov_b32_e32 v75, 0
	v_mov_b32_e32 v76, 0
	v_mov_b32_e32 v77, 0
	v_mov_b32_e32 v78, 0
	v_mov_b32_e32 v79, 0
	v_mov_b32_e32 v80, 0
	v_mov_b32_e32 v81, 0
	v_mov_b32_e32 v82, 0
	v_mov_b32_e32 v83, 0
	v_mov_b32_e32 v84, 0
	v_mov_b32_e32 v85, 0
	v_mov_b32_e32 v86, 0
	v_mov_b32_e32 v87, 0
	v_mov_b32_e32 v88, 0
	v_mov_b32_e32 v89, 0
	v_mov_b32_e32 v90, 0
	v_mov_b32_e32 v91, 0
	v_mov_b32_e32 v92, 0
	v_mov_b32_e32 v93, 0
	v_mov_b32_e32 v94, 0
	v_mov_b32_e32 v95, 0
	v_mov_b32_e32 v98, 0
	v_mov_b32_e32 v99, 0
	v_mov_b32_e32 v100, 0
	v_mov_b32_e32 v101, 0
	v_mov_b32_e32 v102, 0
	v_mov_b32_e32 v103, 0
	v_mov_b32_e32 v104, 0
	v_mov_b32_e32 v105, 0
	v_mov_b32_e32 v106, 0
	v_mov_b32_e32 v107, 0
	v_mov_b32_e32 v108, 0
	v_mov_b32_e32 v109, 0
	v_mov_b32_e32 v110, 0
	v_mov_b32_e32 v111, 0
	v_mov_b32_e32 v112, 0
	v_mov_b32_e32 v113, 0
	v_mov_b32_e32 v114, 0
	v_mov_b32_e32 v115, 0
	v_mov_b32_e32 v116, 0
	v_mov_b32_e32 v117, 0
	v_mov_b32_e32 v118, 0
	v_mov_b32_e32 v119, 0
	v_mov_b32_e32 v120, 0
	v_mov_b32_e32 v121, 0
	v_mov_b32_e32 v122, 0
	v_mov_b32_e32 v123, 0
	v_mov_b32_e32 v124, 0
	v_mov_b32_e32 v125, 0
	v_mov_b32_e32 v126, 0
	v_mov_b32_e32 v127, 0
	v_mov_b32_e32 v128, 0
	v_mov_b32_e32 v129, 0
	v_readlane_b32 vcc_lo, v232, 58
	s_cmp_eq_u32 vcc_lo, 0
	s_cbranch_scc1 .Lsb_done_g
	v_readfirstlane_b32 vcc_hi, v152
	s_cmp_lt_u32 vcc_hi, 64
	s_cbranch_scc0 .Lsb_wait_g
	s_waitcnt vmcnt(0)
	v_readfirstlane_b32 vcc_lo, v210
	s_and_b32 vcc_hi, vcc_lo, 31
	s_cmp_eq_u32 vcc_hi, 31
	s_cbranch_scc1 .Lsb_got_g
	s_or_b32 vcc_lo, vcc_lo, 31
	s_add_u32 vcc_lo, vcc_lo, 1
	v_mov_b32_e32 v211, vcc_lo
	v_readlane_b32 s100, v234, 34
	v_readlane_b32 s101, v234, 35
	s_mov_b32 m0, 0
	s_nop 4

.LBB0_332:
	s_add_u32 s42, s42, 0x80
	s_addc_u32 s43, s43, 0
	s_add_u32 s48, s78, 0x100
	s_addc_u32 s49, s79, 0
	s_mov_b32 s50, 0
	v_readlane_b32 s51, v232, 60
	s_cmp_eq_u32 s51, 0
	s_cbranch_scc0 .Lk_peel
	v_mov_b32_e32 v0, 0
	v_mov_b32_e32 v1, v0
	v_mov_b32_e32 v2, v0
	v_mov_b32_e32 v3, v0
	v_mov_b32_e32 v4, v0
	v_mov_b32_e32 v5, v0
	v_mov_b32_e32 v6, v0
	v_mov_b32_e32 v7, v0
	v_mov_b32_e32 v16, v0
	v_mov_b32_e32 v17, v0
	v_mov_b32_e32 v18, v0
	v_mov_b32_e32 v8, v0
	v_mov_b32_e32 v9, v0
	v_mov_b32_e32 v10, v0
	v_mov_b32_e32 v11, v0
	v_mov_b32_e32 v12, v0
	v_mov_b32_e32 v13, v0
	v_mov_b32_e32 v14, v0
	v_mov_b32_e32 v15, v0
